# P7 q.n: second batch of n loads issued together with the first batch
# speedup vs baseline: 1.0016x; 1.0001x over previous
; DI float bf2f(unsigned short h) { return __uint_as_float(((unsigned)h) << 16); }
; DI void mlstm_out_unit(const Params& p, unsigned char* smem, const int tid, int u) {
;     ...
;     {
;         const int t = tid >> 2, p4 = tid & 3;
;         const bf16_t* qr = q + (tok0 + t) * 128 + p4 * 32;
;         const float* nr = (const float*)(ws + OFF_NU) + ((size_t)bh * 128 + c) * 128 + p4 * 32;
;         float s = 0.f;
; #pragma unroll
;         for (int i = 0; i < 4; ++i) {
;             uint4 a = *(const uint4*)(qr + i * 8);
;             const unsigned* pa = (const unsigned*)&a;
; #pragma unroll
;             for (int e = 0; e < 4; ++e) s += bf2f(pa[e] & 0xffff) * nr[i * 8 + 2 * e] + bf2f(pa[e] >> 16) * nr[i * 8 + 2 * e + 1];
;         }
;         s += __shfl_xor(s, 1, 64); s += __shfl_xor(s, 2, 64);
;         if (p4 == 0) qn[t] = s;
;     }
.LBB0_721:
	s_or_b64 exec, exec, s[86:87]
	v_or_b32_e32 v72, v76, v106
	v_lshlrev_b64 v[66:67], 8, v[72:73]
	v_lshl_add_u64 v[82:83], v[108:109], 0, v[66:67]
	v_lshlrev_b64 v[64:65], 9, v[64:65]
	v_lshl_add_u64 v[74:75], v[110:111], 0, v[64:65]
	global_load_dwordx4 v[64:67], v[82:83], off offset:48
	global_load_dwordx4 v[68:71], v[82:83], off offset:32
	global_load_dwordx4 v[78:81], v[82:83], off offset:16
	s_nop 0
	global_load_dwordx4 v[82:85], v[82:83], off
	s_nop 0
	global_load_dwordx4 v[86:89], v[74:75], off offset:48
	global_load_dwordx4 v[90:93], v[74:75], off offset:32
	global_load_dwordx4 v[130:133], v[74:75], off offset:16
	global_load_dwordx4 v[140:143], v[74:75], off
	global_load_dwordx4 v[188:191], v[74:75], off offset:112
	global_load_dwordx4 v[192:195], v[74:75], off offset:96
	global_load_dwordx4 v[196:199], v[74:75], off offset:80
	global_load_dwordx4 v[200:203], v[74:75], off offset:64
	v_add_u32_e32 v127, 64, v77
	s_waitcnt vmcnt(10)
	v_lshlrev_b32_e32 v94, 16, v68
	v_and_b32_e32 v68, 0xffff0000, v68
	s_waitcnt vmcnt(8)
	v_lshlrev_b32_e32 v72, 16, v82
	v_and_b32_e32 v82, 0xffff0000, v82
	s_waitcnt vmcnt(0)
	v_mul_f32_e32 v82, v141, v82
	v_fmac_f32_e32 v82, v140, v72
	v_add_f32_e32 v72, 0, v82
	v_lshlrev_b32_e32 v82, 16, v83
	v_and_b32_e32 v83, 0xffff0000, v83
	v_mul_f32_e32 v83, v143, v83
	v_fmac_f32_e32 v83, v142, v82
	v_add_f32_e32 v72, v72, v83
	v_and_b32_e32 v83, 0xffff0000, v84
	v_lshlrev_b32_e32 v82, 16, v84
	v_mul_f32_e32 v83, v131, v83
	v_fmac_f32_e32 v83, v130, v82
	v_add_f32_e32 v72, v72, v83
	v_and_b32_e32 v83, 0xffff0000, v85
	v_lshlrev_b32_e32 v82, 16, v85
	v_mul_f32_e32 v83, v133, v83
	v_fmac_f32_e32 v83, v132, v82
	v_lshlrev_b32_e32 v82, 16, v78
	v_and_b32_e32 v78, 0xffff0000, v78
	v_mul_f32_e32 v78, v91, v78
	v_add_f32_e32 v72, v72, v83
	v_fmac_f32_e32 v78, v90, v82
	v_add_f32_e32 v72, v72, v78
	v_lshlrev_b32_e32 v78, 16, v79
	v_and_b32_e32 v79, 0xffff0000, v79
	v_mul_f32_e32 v79, v93, v79
	v_fmac_f32_e32 v79, v92, v78
	v_add_f32_e32 v72, v72, v79
	v_and_b32_e32 v79, 0xffff0000, v80
	v_lshlrev_b32_e32 v78, 16, v80
	v_mul_f32_e32 v79, v87, v79
	v_fmac_f32_e32 v79, v86, v78
	v_add_f32_e32 v72, v72, v79
	v_and_b32_e32 v79, 0xffff0000, v81
	v_lshlrev_b32_e32 v78, 16, v81
	v_mul_f32_e32 v79, v89, v79
	v_fmac_f32_e32 v79, v88, v78
	v_add_f32_e32 v72, v72, v79
	v_mov_b64_e32 v[78:79], v[188:189]
	v_mov_b64_e32 v[80:81], v[190:191]
	v_mov_b64_e32 v[82:83], v[192:193]
	v_mov_b64_e32 v[84:85], v[194:195]
	v_mov_b64_e32 v[86:87], v[196:197]
	v_mov_b64_e32 v[88:89], v[198:199]
	v_mov_b64_e32 v[90:91], v[200:201]
	v_mov_b64_e32 v[92:93], v[202:203]
	v_mul_f32_e32 v68, v91, v68
	v_fmac_f32_e32 v68, v90, v94
	v_add_f32_e32 v68, v72, v68
	v_lshlrev_b32_e32 v72, 16, v69
	v_and_b32_e32 v69, 0xffff0000, v69
	v_mul_f32_e32 v69, v93, v69
	v_fmac_f32_e32 v69, v92, v72
	v_add_f32_e32 v68, v68, v69
	v_lshlrev_b32_e32 v69, 16, v70
	v_and_b32_e32 v70, 0xffff0000, v70
	v_mul_f32_e32 v70, v87, v70
	v_fmac_f32_e32 v70, v86, v69
	v_add_f32_e32 v68, v68, v70
	v_and_b32_e32 v70, 0xffff0000, v71
	v_lshlrev_b32_e32 v69, 16, v71
	v_mul_f32_e32 v70, v89, v70
	v_fmac_f32_e32 v70, v88, v69
	v_lshlrev_b32_e32 v69, 16, v64
	v_and_b32_e32 v64, 0xffff0000, v64
	v_mul_f32_e32 v64, v83, v64
	v_add_f32_e32 v68, v68, v70
	v_fmac_f32_e32 v64, v82, v69
	v_add_f32_e32 v64, v68, v64
	v_lshlrev_b32_e32 v68, 16, v65
	v_and_b32_e32 v65, 0xffff0000, v65
	v_mul_f32_e32 v65, v85, v65
	v_fmac_f32_e32 v65, v84, v68
	v_add_f32_e32 v64, v64, v65
	v_lshlrev_b32_e32 v65, 16, v66
	v_and_b32_e32 v66, 0xffff0000, v66
	v_mul_f32_e32 v66, v79, v66
	v_fmac_f32_e32 v66, v78, v65
	v_add_f32_e32 v64, v64, v66
	v_and_b32_e32 v66, 0xffff0000, v67
	v_lshlrev_b32_e32 v65, 16, v67
	v_mul_f32_e32 v66, v81, v66
	v_fmac_f32_e32 v66, v80, v65
	v_xor_b32_e32 v65, 1, v100
	v_cmp_lt_i32_e32 vcc, v65, v127
	v_add_f32_e32 v64, v64, v66
	s_nop 0
	v_cndmask_b32_e32 v65, v100, v65, vcc
	v_lshlrev_b32_e32 v65, 2, v65
	ds_bpermute_b32 v65, v65, v64
	s_waitcnt lgkmcnt(0)
	v_add_f32_e32 v64, v64, v65
	v_xor_b32_e32 v65, 2, v100
	v_cmp_lt_i32_e32 vcc, v65, v127
	s_nop 1
	v_cndmask_b32_e32 v65, v100, v65, vcc
	v_lshlrev_b32_e32 v65, 2, v65
	ds_bpermute_b32 v65, v65, v64
	s_and_saveexec_b64 s[86:87], s[16:17]
	s_cbranch_execz .LBB0_723
	s_waitcnt lgkmcnt(0)
	v_add_f32_e32 v64, v64, v65
	ds_write_b32 v105, v64 offset:1024
